# static priority raise (s_setprio 1) for waves 4-7 across the attention phases P2 and P5, reset before the grid barrier; on top of v37
# baseline (speedup 1.0000x reference)
; __global__ void __launch_bounds__(512, 2) mega(Params p) {
;     ...
;     for (int rp = 0; rp < REP_P2; ++rp)
;     for (int item = bid; item < 512; item += nb) {
;       const int idx = item & 255;
;       const int pl = idx & 7, rest = idx >> 3;
;       AttArgs a{};
;       int Lp2 = L; asm volatile("" : "+s"(Lp2));
.LBB0_631:
	v_readfirstlane_b32 s100, v224
	s_nop 0
	s_cmpk_lt_u32 s100, 0x100
	s_cbranch_scc1 .Lprio_p2
	s_setprio 1

; DI void xcd_barrier(const XcdBarrier& b) {
;   asm volatile("s_waitcnt vmcnt(0)" ::: "memory");
;   __syncthreads();
;   if (threadIdx.x == 0) {
;     unsigned* bar = b.bar;
;     __builtin_amdgcn_s_waitcnt(0);
;     unsigned nloc = b.st[0], nx = b.st[1];
;     if (nloc == 0u) { xcd_barrier_complete(bar, b.x, nloc, nx); b.st[0] = nloc; b.st[1] = nx; }
.LBB0_850:
	s_setprio 0
	s_waitcnt vmcnt(0)
	s_barrier
	s_mov_b64 s[0:1], exec
	v_readlane_b32 s2, v252, 3
	v_readlane_b32 s3, v252, 4
	s_and_b64 s[2:3], s[0:1], s[2:3]
	s_mov_b64 exec, s[2:3]
	s_cbranch_execz .LBB0_902
	v_mov_b32_e32 v0, 0x21000
	s_waitcnt vmcnt(0) expcnt(0) lgkmcnt(0)
	ds_read_b32 v3, v0
	v_mov_b32_e32 v0, 0x21004
	ds_read_b32 v0, v0
	s_waitcnt lgkmcnt(1)
	v_cmp_ne_u32_e32 vcc, 0, v3
	s_cbranch_vccnz .LBB0_866
	s_mov_b32 s8, 1
	s_branch .LBB0_854

; #define GSYNC() do { for (int _r = 0; _r < REP_SYNC; ++_r) xcd_barrier(xbar); } while (0)
; __global__ void __launch_bounds__(512, 2) mega(Params p) {
;     ...
;     GSYNC();
;     for (int rp = 0; rp < REP_P4; ++rp)
;     for (int item = bid; item < 256; item += nb) {
.LBB0_1072:
	s_or_b64 exec, exec, s[0:1]
	v_readlane_b32 s0, v253, 38
	v_readlane_b32 s1, v253, 39
	s_andn2_b64 vcc, exec, s[0:1]
	v_readlane_b32 s14, v252, 0
	s_waitcnt lgkmcnt(0)
	s_barrier
	v_readfirstlane_b32 s100, v224
	s_nop 0
	s_cmpk_lt_u32 s100, 0x100
	s_cbranch_scc1 .Lprio_p5
	s_setprio 1
.Lprio_p5:
	s_cbranch_vccz .LBB0_1077
